# A far-full stages: softmax touches only the two unmasked logits per query (register select + 2 exps + one-dword P fragment)
# speedup vs baseline: 1.0055x; 1.0033x over previous
; __device__ __forceinline__ float ex2(float x) { return __builtin_amdgcn_exp2f(x); }
; __device__ __forceinline__ f32x16 mfma32(bf16x8 a, bf16x8 b, f32x16 c) { return __builtin_amdgcn_mfma_f32_32x32x16_bf16(a, b, c, 0, 0, 0); }
; #define LOADK(kf_, cb_) do { _Pragma("unroll") for (int s_ = 0; s_ < 4; ++s_) kf_[s_] = *(const LAS bf16x8*)((cb_) + s_ * 1024); } while (0)
; #define LOADV(vf_, cb_) do { _Pragma("unroll") for (int d_ = 0; d_ < 2; ++d_) _Pragma("unroll") for (int s_ = 0; s_ < 2; ++s_) vf_[d_][s_] = *(const LAS bf16x8*)((cb_) + 4096 + (d_ * 2 + s_) * 1024); } while (0)
; #define SCHED_FENCE() __builtin_amdgcn_sched_barrier(0)
; __device__ __forceinline__ void sm_A(f32x16& sc, float& l, bf16x8& p0, bf16x8& p1) {
; #pragma unroll
;     for (int i = 0; i < 16; ++i) { const float p = ex2(sc[i]); sc[i] = p; l += p; }
;     pack_p(sc, p0, p1);
; }
; __device__ __forceinline__ void pv4(const bf16x8 (&vf)[2][2], bf16x8 p0, bf16x8 p1, f32x16& o0, f32x16& o1) {
;     o0 = mfma32(vf[0][0], p0, o0); o1 = mfma32(vf[1][0], p0, o1); o0 = mfma32(vf[0][1], p1, o0); o1 = mfma32(vf[1][1], p1, o1);
; }
; __device__ __forceinline__ void sub_A(const bf16x8 (&kf)[4], const bf16x8 (&vf)[2][2], const bf16x8 (&qf)[4], f32x16 sc  , f32x16& o0, f32x16& o1, float& l) {
; #pragma unroll
;     for (int s = 0; s < 4; ++s) sc = mfma32(kf[s], qf[s], sc);
;     bf16x8 p0, p1; sm_A(sc, l, p0, p1);
;     pv4(vf, p0, p1, o0, o1);
; }
; __device__ __forceinline__ void blk_A(int b, int hd, int chunk  , const bf16_t* QK, const bf16_t* VT, bf16_t* mixed, LAS unsigned char* lds, const float* tblg, int tid, int lane, int wave) {
;     ...
;         for (int u = 0; u < 2; ++u) {
;             const int kb = 2 * sbk + u; const bool cA = kb <= qbA && kb + 64 >= qbA, cB = kb <= qbB && kb + 64 >= qbB;
;             if (cA || cB) {
;                 bf16x8 kf[4], vf[2][2];
;                 LOADK(kf, cb + u * 8192); LOADV(vf, cb + u * 8192);
;                 if (cA) { f32x16 tA; LOADT(tA, tb - (qbA - kb) * 128); SCHED_FENCE(); sub_A(kf, vf, qfA, tA, oA0, oA1, lA); }
;                 if (cB) { f32x16 tB; LOADT(tB, tb - (qbB - kb) * 128); SCHED_FENCE(); sub_A(kf, vf, qfB, tB, oB0, oB1, lB); }
.LBB0_407:
	s_min_i32 s0, s54, s27
	s_ashr_i32 s1, s0, 31
	s_lshl_b32 s55, s35, 14
	s_lshl_b64 s[18:19], s[0:1], 18
	s_waitcnt lgkmcnt(0)
	v_lshl_add_u64 v[2:3], v[150:151], 0, s[18:19]
	s_add_i32 s18, s31, s55
	s_lshl_b32 s0, s0, 6
	v_lshl_add_u64 v[2:3], v[2:3], 0, s[12:13]
	s_add_i32 m0, s18, 0x8900
	s_ashr_i32 s1, s0, 31
	global_load_lds_dwordx4 v[2:3], off
	v_lshl_add_u64 v[2:3], s[0:1], 1, v[152:153]
	s_add_i32 m0, s18, 0x9900
	s_lshl_b32 s55, s53, 14
	global_load_lds_dwordx4 v[2:3], off
	s_add_i32 s0, s30, 0xffffffc8
	s_cmp_ge_i32 s52, s0
	s_cbranch_scc0 .Lattn_a_slow
	s_cmp_lt_i32 s52, s30
	s_cbranch_scc0 .Lattn_a_slow
	v_add_u32_e32 v0, s55, v179
	s_add_i32 s1, s30, 0xffffffee
	s_cmp_le_i32 s52, s1
	s_cbranch_scc0 .Lattn_a_dense
	v_and_b32_e32 v157, 16, v179
	s_mov_b32 s0, 0xaaaaaaaa
	s_mov_b32 s1, 0xaaaaaaaa
	s_mov_b32 s18, 0xcccccccc
	s_mov_b32 s19, 0xcccccccc
	s_mov_b32 s56, 0xf0f0f0f0
	s_mov_b32 s57, 0xf0f0f0f0
	ds_read_b128 v[144:147], v0 offset:35072
	ds_read_b128 v[140:143], v0 offset:36096
	ds_read_b128 v[136:139], v0 offset:37120
	ds_read_b128 v[132:135], v0 offset:38144
	ds_read_b128 v[80:83], v154 offset:1024
	ds_read_b128 v[84:87], v154 offset:1040
	ds_read_b128 v[88:91], v154 offset:1088
	ds_read_b128 v[92:95], v154 offset:1104
	ds_read_b128 v[206:209], v154 offset:0
	ds_read_b128 v[210:213], v154 offset:16
	ds_read_b128 v[214:217], v154 offset:64
	ds_read_b128 v[218:221], v154 offset:80
	s_waitcnt lgkmcnt(4)
	v_mfma_f32_32x32x16_bf16 v[80:95], v[144:147], v[96:99], v[80:95]
	v_mfma_f32_32x32x16_bf16 v[80:95], v[140:143], v[100:103], v[80:95]
	v_mfma_f32_32x32x16_bf16 v[80:95], v[136:139], v[112:115], v[80:95]
	v_mfma_f32_32x32x16_bf16 v[80:95], v[132:135], v[116:119], v[80:95]
	ds_read_b128 v[128:131], v0 offset:39168
	ds_read_b128 v[6:9], v0 offset:40192
	ds_read_b128 v[10:13], v0 offset:41216
	ds_read_b128 v[2:5], v0 offset:42240
	s_nop 5
	s_waitcnt lgkmcnt(4)
	v_mfma_f32_32x32x16_bf16 v[206:221], v[144:147], v[104:107], v[206:221]
	v_cndmask_b32_e64 v80, v80, v81, s[0:1]
	v_cndmask_b32_e64 v82, v82, v83, s[0:1]
	v_cndmask_b32_e64 v84, v84, v85, s[0:1]
	v_cndmask_b32_e64 v86, v86, v87, s[0:1]
	v_cndmask_b32_e64 v88, v88, v89, s[0:1]
	v_cndmask_b32_e64 v90, v90, v91, s[0:1]
	v_cndmask_b32_e64 v92, v92, v93, s[0:1]
	v_cndmask_b32_e64 v94, v94, v95, s[0:1]
	v_cndmask_b32_e64 v80, v80, v82, s[18:19]
	v_cndmask_b32_e64 v84, v84, v86, s[18:19]
	v_cndmask_b32_e64 v88, v88, v90, s[18:19]
	v_cndmask_b32_e64 v92, v92, v94, s[18:19]
	v_mfma_f32_32x32x16_bf16 v[206:221], v[140:143], v[108:111], v[206:221]
	v_cndmask_b32_e64 v80, v80, v84, s[56:57]
	v_cndmask_b32_e64 v88, v88, v92, s[56:57]
	v_exp_f32_e32 v80, v80
	v_exp_f32_e32 v88, v88
	s_mov_b32 vcc_lo, 0x00ff00ff
	s_mov_b32 vcc_hi, 0xff00ff00
	s_nop 0
	v_cndmask_b32_e32 v80, 0, v80, vcc
	v_cndmask_b32_e32 v88, 0, v88, vcc
	v_add_f32_e32 v156, v156, v80
	v_add_f32_e32 v156, v156, v88
	v_cvt_pk_bf16_f32 v166, v80, 0
	v_mfma_f32_32x32x16_bf16 v[206:221], v[136:139], v[120:123], v[206:221]
	v_cvt_pk_bf16_f32 v167, v88, 0
	v_lshlrev_b32_e32 v166, v157, v166
	v_lshlrev_b32_e32 v167, v157, v167
	s_mov_b32 vcc_lo, 0x03030303
	s_mov_b32 vcc_hi, 0x03030303
	s_nop 0
	v_cndmask_b32_e32 v194, 0, v166, vcc
	v_cndmask_b32_e32 v198, 0, v167, vcc
	s_mov_b32 vcc_lo, 0x0c0c0c0c
	s_mov_b32 vcc_hi, 0x0c0c0c0c
	s_nop 0
	v_cndmask_b32_e32 v195, 0, v166, vcc
	v_mfma_f32_32x32x16_bf16 v[206:221], v[132:135], v[124:127], v[206:221]
	ds_read_b128 v[144:147], v0 offset:43264
	ds_read_b128 v[140:143], v0 offset:44288
	ds_read_b128 v[136:139], v0 offset:45312
	ds_read_b128 v[132:135], v0 offset:46336
	v_cndmask_b32_e32 v199, 0, v167, vcc
	s_mov_b32 vcc_lo, 0x30303030
	s_mov_b32 vcc_hi, 0x30303030
	s_nop 0
	v_cndmask_b32_e32 v196, 0, v166, vcc
	v_cndmask_b32_e32 v200, 0, v167, vcc
	s_mov_b32 vcc_lo, 0xc0c0c0c0
	s_mov_b32 vcc_hi, 0xc0c0c0c0
	s_nop 0
	v_cndmask_b32_e32 v197, 0, v166, vcc
	v_cndmask_b32_e32 v201, 0, v167, vcc
	ds_read_b128 v[80:83], v154 offset:1152
	ds_read_b128 v[84:87], v154 offset:1168
	ds_read_b128 v[88:91], v154 offset:1216
	ds_read_b128 v[92:95], v154 offset:1232
	s_waitcnt lgkmcnt(8)
	v_mfma_f32_32x32x16_bf16 v[64:79], v[128:131], v[194:197], v[64:79]
	v_cndmask_b32_e64 v206, v206, v207, s[0:1]
	v_cndmask_b32_e64 v208, v208, v209, s[0:1]
	v_cndmask_b32_e64 v210, v210, v211, s[0:1]
	v_cndmask_b32_e64 v212, v212, v213, s[0:1]
	v_cndmask_b32_e64 v214, v214, v215, s[0:1]
	v_cndmask_b32_e64 v216, v216, v217, s[0:1]
	v_mfma_f32_32x32x16_bf16 v[48:63], v[10:13], v[194:197], v[48:63]
	v_cndmask_b32_e64 v218, v218, v219, s[0:1]
	v_cndmask_b32_e64 v220, v220, v221, s[0:1]
	v_cndmask_b32_e64 v206, v206, v208, s[18:19]
	v_cndmask_b32_e64 v210, v210, v212, s[18:19]
	v_cndmask_b32_e64 v214, v214, v216, s[18:19]
	v_cndmask_b32_e64 v218, v218, v220, s[18:19]
	v_mfma_f32_32x32x16_bf16 v[64:79], v[6:9], v[198:201], v[64:79]
	v_cndmask_b32_e64 v206, v206, v210, s[56:57]
	v_cndmask_b32_e64 v214, v214, v218, s[56:57]
	v_exp_f32_e32 v206, v206
	v_exp_f32_e32 v214, v214
	s_mov_b32 vcc_lo, 0x00ff00ff
	s_mov_b32 vcc_hi, 0xff00ff00
	v_mfma_f32_32x32x16_bf16 v[48:63], v[2:5], v[198:201], v[48:63]
	s_waitcnt lgkmcnt(0)
; __device__ __forceinline__ float ex2(float x) { return __builtin_amdgcn_exp2f(x); }
; __device__ __forceinline__ f32x16 mfma32(bf16x8 a, bf16x8 b, f32x16 c) { return __builtin_amdgcn_mfma_f32_32x32x16_bf16(a, b, c, 0, 0, 0); }
; __device__ __forceinline__ void sm_A(f32x16& sc, float& l, bf16x8& p0, bf16x8& p1) {
; #pragma unroll
;     for (int i = 0; i < 16; ++i) { const float p = ex2(sc[i]); sc[i] = p; l += p; }
;     pack_p(sc, p0, p1);
; }
; __device__ __forceinline__ void pv4(const bf16x8 (&vf)[2][2], bf16x8 p0, bf16x8 p1, f32x16& o0, f32x16& o1) {
;     o0 = mfma32(vf[0][0], p0, o0); o1 = mfma32(vf[1][0], p0, o1); o0 = mfma32(vf[0][1], p1, o0); o1 = mfma32(vf[1][1], p1, o1);
; }
; __device__ __forceinline__ void sub_A(const bf16x8 (&kf)[4], const bf16x8 (&vf)[2][2], const bf16x8 (&qf)[4], f32x16 sc  , f32x16& o0, f32x16& o1, float& l) {
; #pragma unroll
;     for (int s = 0; s < 4; ++s) sc = mfma32(kf[s], qf[s], sc);
;     bf16x8 p0, p1; sm_A(sc, l, p0, p1);
;     pv4(vf, p0, p1, o0, o1);
; }
	s_nop 0
	v_cndmask_b32_e32 v206, 0, v206, vcc
	v_cndmask_b32_e32 v214, 0, v214, vcc
	v_add_f32_e32 v155, v155, v206
	v_add_f32_e32 v155, v155, v214
	v_cvt_pk_bf16_f32 v166, v206, 0
	v_mfma_f32_32x32x16_bf16 v[80:95], v[144:147], v[96:99], v[80:95]
	v_cvt_pk_bf16_f32 v167, v214, 0
	v_lshlrev_b32_e32 v166, v157, v166
	v_lshlrev_b32_e32 v167, v157, v167
	s_mov_b32 vcc_lo, 0x03030303
	s_mov_b32 vcc_hi, 0x03030303
	s_nop 0
	v_mfma_f32_32x32x16_bf16 v[80:95], v[140:143], v[100:103], v[80:95]
	v_cndmask_b32_e32 v158, 0, v166, vcc
	v_cndmask_b32_e32 v162, 0, v167, vcc
	s_mov_b32 vcc_lo, 0x0c0c0c0c
	s_mov_b32 vcc_hi, 0x0c0c0c0c
	s_nop 0
	v_cndmask_b32_e32 v159, 0, v166, vcc
	v_mfma_f32_32x32x16_bf16 v[80:95], v[136:139], v[112:115], v[80:95]
	v_cndmask_b32_e32 v163, 0, v167, vcc
	s_mov_b32 vcc_lo, 0x30303030
	s_mov_b32 vcc_hi, 0x30303030
	s_nop 0
	v_cndmask_b32_e32 v160, 0, v166, vcc
	v_cndmask_b32_e32 v164, 0, v167, vcc
	v_mfma_f32_32x32x16_bf16 v[80:95], v[132:135], v[116:119], v[80:95]
	s_mov_b32 vcc_lo, 0xc0c0c0c0
	s_mov_b32 vcc_hi, 0xc0c0c0c0
	s_nop 0
	v_cndmask_b32_e32 v161, 0, v166, vcc
	v_cndmask_b32_e32 v165, 0, v167, vcc
	s_nop 7
	ds_read_b128 v[206:209], v154 offset:128
	ds_read_b128 v[210:213], v154 offset:144
	ds_read_b128 v[214:217], v154 offset:192
	ds_read_b128 v[218:221], v154 offset:208
	v_mfma_f32_32x32x16_bf16 v[32:47], v[128:131], v[158:161], v[32:47]
	v_cndmask_b32_e64 v80, v80, v81, s[0:1]
	v_cndmask_b32_e64 v82, v82, v83, s[0:1]
	v_cndmask_b32_e64 v84, v84, v85, s[0:1]
	v_cndmask_b32_e64 v86, v86, v87, s[0:1]
	v_cndmask_b32_e64 v88, v88, v89, s[0:1]
	v_cndmask_b32_e64 v90, v90, v91, s[0:1]
	v_mfma_f32_32x32x16_bf16 v[16:31], v[10:13], v[158:161], v[16:31]
	v_cndmask_b32_e64 v92, v92, v93, s[0:1]
	v_cndmask_b32_e64 v94, v94, v95, s[0:1]
	v_cndmask_b32_e64 v80, v80, v82, s[18:19]
	v_cndmask_b32_e64 v84, v84, v86, s[18:19]
	v_cndmask_b32_e64 v88, v88, v90, s[18:19]
	v_cndmask_b32_e64 v92, v92, v94, s[18:19]
	v_mfma_f32_32x32x16_bf16 v[32:47], v[6:9], v[162:165], v[32:47]
	v_cndmask_b32_e64 v80, v80, v84, s[56:57]
	v_cndmask_b32_e64 v88, v88, v92, s[56:57]
	v_exp_f32_e32 v80, v80
	v_exp_f32_e32 v88, v88
	s_mov_b32 vcc_lo, 0x00ff00ff
	s_mov_b32 vcc_hi, 0xff00ff00
	v_mfma_f32_32x32x16_bf16 v[16:31], v[2:5], v[162:165], v[16:31]
	ds_read_b128 v[128:131], v0 offset:47360
	ds_read_b128 v[6:9], v0 offset:48384
	ds_read_b128 v[10:13], v0 offset:49408
	ds_read_b128 v[2:5], v0 offset:50432
	s_waitcnt lgkmcnt(4)
	s_nop 0
	v_cndmask_b32_e32 v80, 0, v80, vcc
	v_cndmask_b32_e32 v88, 0, v88, vcc
	v_add_f32_e32 v156, v156, v80
	v_add_f32_e32 v156, v156, v88
	v_cvt_pk_bf16_f32 v166, v80, 0
	v_mfma_f32_32x32x16_bf16 v[206:221], v[144:147], v[104:107], v[206:221]
	v_cvt_pk_bf16_f32 v167, v88, 0
	v_lshlrev_b32_e32 v166, v157, v166
	v_lshlrev_b32_e32 v167, v157, v167
	s_mov_b32 vcc_lo, 0x03030303
	s_mov_b32 vcc_hi, 0x03030303
	s_nop 0
	v_mfma_f32_32x32x16_bf16 v[206:221], v[140:143], v[108:111], v[206:221]
	v_cndmask_b32_e32 v194, 0, v166, vcc
	v_cndmask_b32_e32 v198, 0, v167, vcc
	s_mov_b32 vcc_lo, 0x0c0c0c0c
	s_mov_b32 vcc_hi, 0x0c0c0c0c
	s_nop 0
	v_cndmask_b32_e32 v195, 0, v166, vcc
	v_mfma_f32_32x32x16_bf16 v[206:221], v[136:139], v[120:123], v[206:221]
	v_cndmask_b32_e32 v199, 0, v167, vcc
	s_mov_b32 vcc_lo, 0x30303030
	s_mov_b32 vcc_hi, 0x30303030
	s_nop 0
	v_cndmask_b32_e32 v196, 0, v166, vcc
	v_cndmask_b32_e32 v200, 0, v167, vcc
	v_mfma_f32_32x32x16_bf16 v[206:221], v[132:135], v[124:127], v[206:221]
	s_mov_b32 vcc_lo, 0xc0c0c0c0
	s_mov_b32 vcc_hi, 0xc0c0c0c0
	s_nop 0
	v_cndmask_b32_e32 v197, 0, v166, vcc
	v_cndmask_b32_e32 v201, 0, v167, vcc
	s_nop 9
	s_waitcnt lgkmcnt(0)
	v_mfma_f32_32x32x16_bf16 v[64:79], v[128:131], v[194:197], v[64:79]
	v_cndmask_b32_e64 v206, v206, v207, s[0:1]
	v_cndmask_b32_e64 v208, v208, v209, s[0:1]
	v_cndmask_b32_e64 v210, v210, v211, s[0:1]
	v_cndmask_b32_e64 v212, v212, v213, s[0:1]
	v_cndmask_b32_e64 v214, v214, v215, s[0:1]
	v_cndmask_b32_e64 v216, v216, v217, s[0:1]
	v_cndmask_b32_e64 v218, v218, v219, s[0:1]
	v_cndmask_b32_e64 v220, v220, v221, s[0:1]
	v_cndmask_b32_e64 v206, v206, v208, s[18:19]
	v_cndmask_b32_e64 v210, v210, v212, s[18:19]
	v_cndmask_b32_e64 v214, v214, v216, s[18:19]
	v_cndmask_b32_e64 v218, v218, v220, s[18:19]
	v_mfma_f32_32x32x16_bf16 v[48:63], v[10:13], v[194:197], v[48:63]
	v_cndmask_b32_e64 v206, v206, v210, s[56:57]
	v_cndmask_b32_e64 v214, v214, v218, s[56:57]
	v_exp_f32_e32 v206, v206
	v_exp_f32_e32 v214, v214
	s_mov_b32 vcc_lo, 0x00ff00ff
	s_mov_b32 vcc_hi, 0xff00ff00
	s_nop 0
	v_cndmask_b32_e32 v206, 0, v206, vcc
	v_cndmask_b32_e32 v214, 0, v214, vcc
	v_add_f32_e32 v155, v155, v206
	v_add_f32_e32 v155, v155, v214
	v_cvt_pk_bf16_f32 v166, v206, 0
	v_mfma_f32_32x32x16_bf16 v[64:79], v[6:9], v[198:201], v[64:79]
	v_cvt_pk_bf16_f32 v167, v214, 0
	v_lshlrev_b32_e32 v166, v157, v166
	v_lshlrev_b32_e32 v167, v157, v167
	s_mov_b32 vcc_lo, 0x03030303
	s_mov_b32 vcc_hi, 0x03030303
	s_nop 0
	v_cndmask_b32_e32 v158, 0, v166, vcc
	v_cndmask_b32_e32 v162, 0, v167, vcc
	s_mov_b32 vcc_lo, 0x0c0c0c0c
	s_mov_b32 vcc_hi, 0x0c0c0c0c
	s_nop 0
	v_cndmask_b32_e32 v159, 0, v166, vcc
	v_mfma_f32_32x32x16_bf16 v[48:63], v[2:5], v[198:201], v[48:63]
	v_cndmask_b32_e32 v163, 0, v167, vcc
	s_mov_b32 vcc_lo, 0x30303030
	s_mov_b32 vcc_hi, 0x30303030
	s_nop 0
	v_cndmask_b32_e32 v160, 0, v166, vcc
	v_cndmask_b32_e32 v164, 0, v167, vcc
	s_mov_b32 vcc_lo, 0xc0c0c0c0
	s_mov_b32 vcc_hi, 0xc0c0c0c0
	s_nop 0
	v_cndmask_b32_e32 v161, 0, v166, vcc
	v_cndmask_b32_e32 v165, 0, v167, vcc
	s_nop 1
	v_mfma_f32_32x32x16_bf16 v[32:47], v[128:131], v[158:161], v[32:47]
	v_mfma_f32_32x32x16_bf16 v[16:31], v[10:13], v[158:161], v[16:31]
	v_mfma_f32_32x32x16_bf16 v[32:47], v[6:9], v[162:165], v[32:47]
	v_mfma_f32_32x32x16_bf16 v[16:31], v[2:5], v[162:165], v[16:31]
	s_branch .LBB0_417
; __device__ __forceinline__ float ex2(float x) { return __builtin_amdgcn_exp2f(x); }
; __device__ __forceinline__ f32x16 mfma32(bf16x8 a, bf16x8 b, f32x16 c) { return __builtin_amdgcn_mfma_f32_32x32x16_bf16(a, b, c, 0, 0, 0); }
; #define LOADK(kf_, cb_) do { _Pragma("unroll") for (int s_ = 0; s_ < 4; ++s_) kf_[s_] = *(const LAS bf16x8*)((cb_) + s_ * 1024); } while (0)
; #define LOADV(vf_, cb_) do { _Pragma("unroll") for (int d_ = 0; d_ < 2; ++d_) _Pragma("unroll") for (int s_ = 0; s_ < 2; ++s_) vf_[d_][s_] = *(const LAS bf16x8*)((cb_) + 4096 + (d_ * 2 + s_) * 1024); } while (0)
; #define LOADT(t_, tp_) do { const f32x4 a_ = *(const LAS f32x4*)(tp_), b_ = *(const LAS f32x4*)((tp_) + 16), c_ = *(const LAS f32x4*)((tp_) + 64), d_ = *(const LAS f32x4*)((tp_) + 80); \
;     t_ = (f32x16){a_[0], a_[1], a_[2], a_[3], b_[0], b_[1], b_[2], b_[3], c_[0], c_[1], c_[2], c_[3], d_[0], d_[1], d_[2], d_[3]}; } while (0)
; #define SCHED_FENCE() __builtin_amdgcn_sched_barrier(0)
; __device__ __forceinline__ void sm_A(f32x16& sc, float& l, bf16x8& p0, bf16x8& p1) {
; #pragma unroll
;     for (int i = 0; i < 16; ++i) { const float p = ex2(sc[i]); sc[i] = p; l += p; }
;     pack_p(sc, p0, p1);
; }
; __device__ __forceinline__ void pv4(const bf16x8 (&vf)[2][2], bf16x8 p0, bf16x8 p1, f32x16& o0, f32x16& o1) {
;     o0 = mfma32(vf[0][0], p0, o0); o1 = mfma32(vf[1][0], p0, o1); o0 = mfma32(vf[0][1], p1, o0); o1 = mfma32(vf[1][1], p1, o1);
; }
; __device__ __forceinline__ void sub_A(const bf16x8 (&kf)[4], const bf16x8 (&vf)[2][2], const bf16x8 (&qf)[4], f32x16 sc  , f32x16& o0, f32x16& o1, float& l) {
; #pragma unroll
;     for (int s = 0; s < 4; ++s) sc = mfma32(kf[s], qf[s], sc);
;     bf16x8 p0, p1; sm_A(sc, l, p0, p1);
;     pv4(vf, p0, p1, o0, o1);
; }
; __device__ __forceinline__ void blk_A(int b, int hd, int chunk  , const bf16_t* QK, const bf16_t* VT, bf16_t* mixed, LAS unsigned char* lds, const float* tblg, int tid, int lane, int wave) {
;     ...
;                 LOADK(kf, cb + u * 8192); LOADV(vf, cb + u * 8192);
;                 if (cA) { f32x16 tA; LOADT(tA, tb - (qbA - kb) * 128); SCHED_FENCE(); sub_A(kf, vf, qfA, tA, oA0, oA1, lA); }
;                 if (cB) { f32x16 tB; LOADT(tB, tb - (qbB - kb) * 128); SCHED_FENCE(); sub_A(kf, vf, qfB, tB, oB0, oB1, lB); }
.Lattn_a_dense:
	ds_read_b128 v[144:147], v0 offset:35072
	ds_read_b128 v[140:143], v0 offset:36096
	ds_read_b128 v[136:139], v0 offset:37120
	ds_read_b128 v[132:135], v0 offset:38144
	ds_read_b128 v[80:83], v154 offset:1024
	ds_read_b128 v[84:87], v154 offset:1040
	ds_read_b128 v[88:91], v154 offset:1088
	ds_read_b128 v[92:95], v154 offset:1104
	ds_read_b128 v[206:209], v154 offset:0
	ds_read_b128 v[210:213], v154 offset:16
	ds_read_b128 v[214:217], v154 offset:64
	ds_read_b128 v[218:221], v154 offset:80
	s_waitcnt lgkmcnt(4)
	v_mfma_f32_32x32x16_bf16 v[80:95], v[144:147], v[96:99], v[80:95]
	v_mfma_f32_32x32x16_bf16 v[80:95], v[140:143], v[100:103], v[80:95]
	v_mfma_f32_32x32x16_bf16 v[80:95], v[136:139], v[112:115], v[80:95]
	v_mfma_f32_32x32x16_bf16 v[80:95], v[132:135], v[116:119], v[80:95]
	ds_read_b128 v[128:131], v0 offset:39168
	ds_read_b128 v[6:9], v0 offset:40192
	ds_read_b128 v[10:13], v0 offset:41216
	ds_read_b128 v[2:5], v0 offset:42240
	s_nop 5
	s_waitcnt lgkmcnt(4)
	v_mfma_f32_32x32x16_bf16 v[206:221], v[144:147], v[104:107], v[206:221]
	v_exp_f32_e32 v80, v80
	v_exp_f32_e32 v81, v81
	v_exp_f32_e32 v82, v82
	v_exp_f32_e32 v83, v83
	v_add_f32_e32 v156, v80, v156
	v_add_f32_e32 v156, v81, v156
	v_add_f32_e32 v156, v82, v156
	v_add_f32_e32 v156, v83, v156
	v_cvt_pk_bf16_f32 v194, v80, v81
	v_cvt_pk_bf16_f32 v195, v82, v83
	v_mfma_f32_32x32x16_bf16 v[206:221], v[140:143], v[108:111], v[206:221]
	v_exp_f32_e32 v84, v84
	v_exp_f32_e32 v85, v85
	v_exp_f32_e32 v86, v86
	v_exp_f32_e32 v87, v87
	v_add_f32_e32 v156, v84, v156
	v_add_f32_e32 v156, v85, v156
	v_add_f32_e32 v156, v86, v156
	v_add_f32_e32 v156, v87, v156
	v_cvt_pk_bf16_f32 v196, v84, v85
	v_cvt_pk_bf16_f32 v197, v86, v87
	v_mfma_f32_32x32x16_bf16 v[206:221], v[136:139], v[120:123], v[206:221]
	v_exp_f32_e32 v88, v88
	v_exp_f32_e32 v89, v89
	v_exp_f32_e32 v90, v90
	v_exp_f32_e32 v91, v91
	v_add_f32_e32 v156, v88, v156
	v_add_f32_e32 v156, v89, v156
	v_add_f32_e32 v156, v90, v156
	v_add_f32_e32 v156, v91, v156
	v_cvt_pk_bf16_f32 v198, v88, v89
	v_cvt_pk_bf16_f32 v199, v90, v91
	v_mfma_f32_32x32x16_bf16 v[206:221], v[132:135], v[124:127], v[206:221]
	ds_read_b128 v[144:147], v0 offset:43264
	ds_read_b128 v[140:143], v0 offset:44288
	ds_read_b128 v[136:139], v0 offset:45312
	ds_read_b128 v[132:135], v0 offset:46336
	v_exp_f32_e32 v92, v92
	v_exp_f32_e32 v93, v93
	v_exp_f32_e32 v94, v94
	v_exp_f32_e32 v95, v95
	v_add_f32_e32 v156, v92, v156
	v_add_f32_e32 v156, v93, v156
	v_add_f32_e32 v156, v94, v156
	v_add_f32_e32 v156, v95, v156
	v_cvt_pk_bf16_f32 v200, v92, v93
	v_cvt_pk_bf16_f32 v201, v94, v95
	ds_read_b128 v[80:83], v154 offset:1152
	ds_read_b128 v[84:87], v154 offset:1168
	ds_read_b128 v[88:91], v154 offset:1216
	ds_read_b128 v[92:95], v154 offset:1232
	s_waitcnt lgkmcnt(8)
	v_mfma_f32_32x32x16_bf16 v[64:79], v[128:131], v[194:197], v[64:79]
	v_exp_f32_e32 v206, v206
	v_exp_f32_e32 v207, v207
	v_exp_f32_e32 v208, v208
	v_exp_f32_e32 v209, v209
	v_mfma_f32_32x32x16_bf16 v[48:63], v[10:13], v[194:197], v[48:63]
	v_add_f32_e32 v155, v206, v155
	v_add_f32_e32 v155, v207, v155
	v_add_f32_e32 v155, v208, v155
	v_add_f32_e32 v155, v209, v155
	v_cvt_pk_bf16_f32 v158, v206, v207
	v_cvt_pk_bf16_f32 v159, v208, v209
	v_mfma_f32_32x32x16_bf16 v[64:79], v[6:9], v[198:201], v[64:79]
	v_exp_f32_e32 v210, v210
	v_exp_f32_e32 v211, v211
	v_exp_f32_e32 v212, v212
	v_exp_f32_e32 v213, v213
	v_mfma_f32_32x32x16_bf16 v[48:63], v[2:5], v[198:201], v[48:63]
	s_waitcnt lgkmcnt(0)
; __device__ __forceinline__ float ex2(float x) { return __builtin_amdgcn_exp2f(x); }
; __device__ __forceinline__ f32x16 mfma32(bf16x8 a, bf16x8 b, f32x16 c) { return __builtin_amdgcn_mfma_f32_32x32x16_bf16(a, b, c, 0, 0, 0); }
; __device__ __forceinline__ void sm_A(f32x16& sc, float& l, bf16x8& p0, bf16x8& p1) {
; #pragma unroll
;     for (int i = 0; i < 16; ++i) { const float p = ex2(sc[i]); sc[i] = p; l += p; }
;     pack_p(sc, p0, p1);
; }
; __device__ __forceinline__ void pv4(const bf16x8 (&vf)[2][2], bf16x8 p0, bf16x8 p1, f32x16& o0, f32x16& o1) {
;     o0 = mfma32(vf[0][0], p0, o0); o1 = mfma32(vf[1][0], p0, o1); o0 = mfma32(vf[0][1], p1, o0); o1 = mfma32(vf[1][1], p1, o1);
; }
; __device__ __forceinline__ void sub_A(const bf16x8 (&kf)[4], const bf16x8 (&vf)[2][2], const bf16x8 (&qf)[4], f32x16 sc  , f32x16& o0, f32x16& o1, float& l) {
; #pragma unroll
;     for (int s = 0; s < 4; ++s) sc = mfma32(kf[s], qf[s], sc);
;     bf16x8 p0, p1; sm_A(sc, l, p0, p1);
;     pv4(vf, p0, p1, o0, o1);
; }
	v_add_f32_e32 v155, v210, v155
	v_add_f32_e32 v155, v211, v155
	v_add_f32_e32 v155, v212, v155
	v_add_f32_e32 v155, v213, v155
	v_cvt_pk_bf16_f32 v160, v210, v211
	v_cvt_pk_bf16_f32 v161, v212, v213
	v_mfma_f32_32x32x16_bf16 v[80:95], v[144:147], v[96:99], v[80:95]
	v_exp_f32_e32 v214, v214
	v_exp_f32_e32 v215, v215
	v_exp_f32_e32 v216, v216
	v_exp_f32_e32 v217, v217
	v_mfma_f32_32x32x16_bf16 v[80:95], v[140:143], v[100:103], v[80:95]
	v_add_f32_e32 v155, v214, v155
	v_add_f32_e32 v155, v215, v155
	v_add_f32_e32 v155, v216, v155
	v_add_f32_e32 v155, v217, v155
	v_cvt_pk_bf16_f32 v162, v214, v215
	v_cvt_pk_bf16_f32 v163, v216, v217
	v_mfma_f32_32x32x16_bf16 v[80:95], v[136:139], v[112:115], v[80:95]
	v_exp_f32_e32 v218, v218
	v_exp_f32_e32 v219, v219
	v_exp_f32_e32 v220, v220
	v_exp_f32_e32 v221, v221
	v_mfma_f32_32x32x16_bf16 v[80:95], v[132:135], v[116:119], v[80:95]
	v_add_f32_e32 v155, v218, v155
	v_add_f32_e32 v155, v219, v155
	v_add_f32_e32 v155, v220, v155
	v_add_f32_e32 v155, v221, v155
	v_cvt_pk_bf16_f32 v164, v218, v219
	v_cvt_pk_bf16_f32 v165, v220, v221
	ds_read_b128 v[206:209], v154 offset:128
	ds_read_b128 v[210:213], v154 offset:144
	ds_read_b128 v[214:217], v154 offset:192
	ds_read_b128 v[218:221], v154 offset:208
	s_nop 3
	v_mfma_f32_32x32x16_bf16 v[32:47], v[128:131], v[158:161], v[32:47]
	v_exp_f32_e32 v80, v80
	v_exp_f32_e32 v81, v81
	v_exp_f32_e32 v82, v82
	v_exp_f32_e32 v83, v83
	v_mfma_f32_32x32x16_bf16 v[16:31], v[10:13], v[158:161], v[16:31]
	v_add_f32_e32 v156, v80, v156
	v_add_f32_e32 v156, v81, v156
	v_add_f32_e32 v156, v82, v156
	v_add_f32_e32 v156, v83, v156
	v_cvt_pk_bf16_f32 v194, v80, v81
	v_cvt_pk_bf16_f32 v195, v82, v83
	v_mfma_f32_32x32x16_bf16 v[32:47], v[6:9], v[162:165], v[32:47]
	v_exp_f32_e32 v84, v84
	v_exp_f32_e32 v85, v85
	v_exp_f32_e32 v86, v86
	v_exp_f32_e32 v87, v87
	v_mfma_f32_32x32x16_bf16 v[16:31], v[2:5], v[162:165], v[16:31]
	ds_read_b128 v[128:131], v0 offset:47360
	ds_read_b128 v[6:9], v0 offset:48384
	ds_read_b128 v[10:13], v0 offset:49408
	ds_read_b128 v[2:5], v0 offset:50432
	s_waitcnt lgkmcnt(4)
	v_add_f32_e32 v156, v84, v156
	v_add_f32_e32 v156, v85, v156
	v_add_f32_e32 v156, v86, v156
	v_add_f32_e32 v156, v87, v156
	v_cvt_pk_bf16_f32 v196, v84, v85
	v_cvt_pk_bf16_f32 v197, v86, v87
	v_mfma_f32_32x32x16_bf16 v[206:221], v[144:147], v[104:107], v[206:221]
	v_exp_f32_e32 v88, v88
	v_exp_f32_e32 v89, v89
	v_exp_f32_e32 v90, v90
	v_exp_f32_e32 v91, v91
	v_mfma_f32_32x32x16_bf16 v[206:221], v[140:143], v[108:111], v[206:221]
	v_add_f32_e32 v156, v88, v156
	v_add_f32_e32 v156, v89, v156
	v_add_f32_e32 v156, v90, v156
	v_add_f32_e32 v156, v91, v156
	v_cvt_pk_bf16_f32 v198, v88, v89
	v_cvt_pk_bf16_f32 v199, v90, v91
	v_mfma_f32_32x32x16_bf16 v[206:221], v[136:139], v[120:123], v[206:221]
	v_exp_f32_e32 v92, v92
	v_exp_f32_e32 v93, v93
	v_exp_f32_e32 v94, v94
	v_exp_f32_e32 v95, v95
	v_mfma_f32_32x32x16_bf16 v[206:221], v[132:135], v[124:127], v[206:221]
	v_add_f32_e32 v156, v92, v156
	v_add_f32_e32 v156, v93, v156
	v_add_f32_e32 v156, v94, v156
	v_add_f32_e32 v156, v95, v156
	v_cvt_pk_bf16_f32 v200, v92, v93
	v_cvt_pk_bf16_f32 v201, v94, v95
	s_nop 5
	s_waitcnt lgkmcnt(0)
	v_mfma_f32_32x32x16_bf16 v[64:79], v[128:131], v[194:197], v[64:79]
	v_exp_f32_e32 v206, v206
	v_exp_f32_e32 v207, v207
	v_exp_f32_e32 v208, v208
	v_exp_f32_e32 v209, v209
	v_add_f32_e32 v155, v206, v155
	v_add_f32_e32 v155, v207, v155
	v_add_f32_e32 v155, v208, v155
	v_add_f32_e32 v155, v209, v155
	v_cvt_pk_bf16_f32 v158, v206, v207
	v_cvt_pk_bf16_f32 v159, v208, v209
	v_mfma_f32_32x32x16_bf16 v[48:63], v[10:13], v[194:197], v[48:63]
	v_exp_f32_e32 v210, v210
	v_exp_f32_e32 v211, v211
	v_exp_f32_e32 v212, v212
	v_exp_f32_e32 v213, v213
	v_add_f32_e32 v155, v210, v155
	v_add_f32_e32 v155, v211, v155
	v_add_f32_e32 v155, v212, v155
	v_add_f32_e32 v155, v213, v155
	v_cvt_pk_bf16_f32 v160, v210, v211
	v_cvt_pk_bf16_f32 v161, v212, v213
	v_mfma_f32_32x32x16_bf16 v[64:79], v[6:9], v[198:201], v[64:79]
	v_exp_f32_e32 v214, v214
	v_exp_f32_e32 v215, v215
	v_exp_f32_e32 v216, v216
	v_exp_f32_e32 v217, v217
	v_add_f32_e32 v155, v214, v155
	v_add_f32_e32 v155, v215, v155
	v_add_f32_e32 v155, v216, v155
	v_add_f32_e32 v155, v217, v155
	v_cvt_pk_bf16_f32 v162, v214, v215
	v_cvt_pk_bf16_f32 v163, v216, v217
	v_mfma_f32_32x32x16_bf16 v[48:63], v[2:5], v[198:201], v[48:63]
	v_exp_f32_e32 v218, v218
	v_exp_f32_e32 v219, v219
	v_exp_f32_e32 v220, v220
	v_exp_f32_e32 v221, v221
	v_add_f32_e32 v155, v218, v155
	v_add_f32_e32 v155, v219, v155
	v_add_f32_e32 v155, v220, v155
	v_add_f32_e32 v155, v221, v155
	v_cvt_pk_bf16_f32 v164, v218, v219
	v_cvt_pk_bf16_f32 v165, v220, v221
	v_mfma_f32_32x32x16_bf16 v[32:47], v[128:131], v[158:161], v[32:47]
	v_mfma_f32_32x32x16_bf16 v[16:31], v[10:13], v[158:161], v[16:31]
	v_mfma_f32_32x32x16_bf16 v[32:47], v[6:9], v[162:165], v[32:47]
	v_mfma_f32_32x32x16_bf16 v[16:31], v[2:5], v[162:165], v[16:31]
	s_branch .LBB0_417
